# ret_out_item: stage-1 V-chunk loads issued as one batch with counted vmcnt, plus output-stage gate/weight loads hoisted (Ph5 work-queue items ~20us shorter per queue pass)
# baseline (speedup 1.0000x reference)
; #define LAS __attribute__((address_space(3)))
; __device__ __forceinline__ void ret_out_item(LAS unsigned char* lds, const bf16* Z, const bf16* AT, const float* gn, bf16* MIXED, int b, int c, const float* lgs) {
;     LAS bf16* VT4 = (LAS bf16*)lds;
;     const int tid_ = my_tid(lds); const int tid = tid_, lane = tid & 63, r32 = lane & 31, hi = lane >> 5; const int wid = __builtin_amdgcn_readfirstlane(tid >> 6);
;     const int rowbase = b * SEQ + 64 * c;
; #pragma unroll
;     for (int i = 0; i < 8; ++i) { const int ci = tid + 512 * i, l = ci & 63, ec = ci >> 6; const u32x4 vr = *(const u32x4*)(Z + (size_t)(rowbase + l) * NZ + ZC_RV + ec * 8);
; #pragma unroll
;         for (int e = 0; e < 4; ++e) { const unsigned vw = vr[e]; VT4[(8 * ec + 2 * e) * 72 + l] = (bf16)(vw & 0xffffu); VT4[(8 * ec + 2 * e + 1) * 72 + l] = (bf16)(vw >> 16); } }
;     __syncthreads();
.LBB0_678:
	s_and_b64 vcc, exec, s[2:3]
	s_cbranch_vccz .LBB0_682
	v_mov_b32_e32 v1, s45
	ds_read_b64 v[2:3], v1
	s_sub_i32 s3, s57, 32
	v_readlane_b32 s2, v254, 10
	ds_read_b64 v[6:7], v1
	s_movk_i32 s16, 0xa00
	s_waitcnt lgkmcnt(0)
	v_readfirstlane_b32 s4, v2
	v_mov_b32_e32 v4, s2
	v_readfirstlane_b32 s2, v3
	s_add_u32 s4, s4, 0x6800000
	s_addc_u32 s5, s2, 0
	ds_read_b64 v[2:3], v4
	ds_read_b64 v[4:5], v1
	s_getreg_b32 s2, hwreg(HW_REG_HW_ID, 0, 6)
	s_lshl_b32 s2, s2, 2
	s_and_b32 s2, s2, 0xfc
	s_add_i32 s2, s2, 0
	s_add_i32 s2, s2, 0x25a00
	v_mov_b32_e32 v1, s2
	ds_read_b32 v1, v1
	s_lshr_b32 s2, s3, 8
	s_and_b32 s3, s3, 0xff
	s_lshl_b32 s7, s3, 6
	v_mov_b32_e32 v9, v0
	s_waitcnt lgkmcnt(0)
	v_readfirstlane_b32 s6, v1
	v_mbcnt_lo_u32_b32 v1, -1, 0
	v_mbcnt_hi_u32_b32 v1, -1, v1
	v_readfirstlane_b32 s14, v6
	v_and_b32_e32 v16, 63, v1
	v_lshl_add_u32 v18, s6, 6, v1
	s_lshl_b32 s6, s2, 14
	s_or_b32 s13, s7, s6
	v_or_b32_e32 v8, s13, v16
	v_mul_lo_u32 v8, v8, s16
	v_lshl_add_u64 v[12:13], v[8:9], 1, s[4:5]
	v_ashrrev_i32_e32 v8, 3, v18
	v_and_b32_e32 v14, -8, v8
	v_ashrrev_i32_e32 v15, 31, v14
	v_lshl_add_u64 v[8:9], v[14:15], 1, v[12:13]
	global_load_dwordx4 v[64:67], v[8:9], off offset:2880
	v_add_u32_e32 v15, 0x200, v18
	v_ashrrev_i32_e32 v15, 3, v15
	v_lshlrev_b32_e32 v19, 1, v16
	v_mul_lo_u32 v16, v14, s87
	v_and_b32_e32 v14, -8, v15
	v_add3_u32 v20, 0, v16, v19
	v_ashrrev_i32_e32 v15, 31, v14
	v_lshl_add_u64 v[16:17], v[14:15], 1, v[12:13]
	v_add_u32_e32 v15, 0x400, v18
	v_ashrrev_i32_e32 v15, 3, v15
	v_mul_lo_u32 v14, v14, s87
	v_readfirstlane_b32 s6, v18
	s_ashr_i32 s15, s6, 7
	s_bfe_u32 s12, s6, 0x10006
	s_cmp_eq_u32 s15, 1
	s_cselect_b64 vcc, -1, 0
	s_cmp_lg_u32 s15, 2
	v_cndmask_b32_e32 v6, v161, v162, vcc
	s_cselect_b64 vcc, -1, 0
	s_cmp_lg_u32 s15, 3
	v_cndmask_b32_e32 v42, v163, v6, vcc
	s_cselect_b64 vcc, -1, 0
	s_lshl_b32 s2, s2, 10
	s_lshl_b32 s3, s3, 2
	s_or_b32 s2, s3, s2
	s_and_b32 s6, s6, 0xffffff80
	s_add_i32 s2, s2, s15
	s_ashr_i32 s7, s6, 31
	s_ashr_i32 s3, s2, 31
	s_lshl_b64 s[8:9], s[6:7], 1
	s_lshl_b64 s[2:3], s[2:3], 15
	v_readfirstlane_b32 s11, v7
	v_bfe_u32 v143, v1, 5, 1
	s_add_u32 s2, s14, s2
	v_mov_b32_e32 v141, v0
	v_and_b32_e32 v62, 31, v1
	v_lshlrev_b32_e32 v140, 4, v143
	s_addc_u32 s3, s11, s3
	v_lshl_add_u64 v[6:7], s[2:3], 0, v[140:141]
	s_mov_b32 s10, 0x17e00000
	v_lshl_or_b32 v144, s12, 5, v62
	v_or_b32_e32 v142, s13, v144
	v_readfirstlane_b32 s11, v2
	v_lshlrev_b32_e32 v138, 3, v143
	v_mov_b32_e32 v139, v0
	v_mov_b32_e32 v96, v20
	global_load_dwordx4 v[68:71], v[16:17], off offset:2880
	v_and_b32_e32 v16, -8, v15
	v_ashrrev_i32_e32 v17, 31, v16
	v_add3_u32 v20, 0, v14, v19
	v_lshl_add_u64 v[14:15], v[16:17], 1, v[12:13]
	v_mul_lo_u32 v16, v16, s87
	v_mov_b32_e32 v97, v20
	global_load_dwordx4 v[72:75], v[14:15], off offset:2880
	v_add_u32_e32 v14, 0x600, v18
	v_ashrrev_i32_e32 v14, 3, v14
	v_and_b32_e32 v14, -8, v14
	v_ashrrev_i32_e32 v15, 31, v14
	v_add3_u32 v20, 0, v16, v19
	v_lshl_add_u64 v[16:17], v[14:15], 1, v[12:13]
	v_add_u32_e32 v15, 0x800, v18
	v_ashrrev_i32_e32 v15, 3, v15
	v_mul_lo_u32 v14, v14, s87
	v_mov_b32_e32 v98, v20
	global_load_dwordx4 v[76:79], v[16:17], off offset:2880
	v_and_b32_e32 v16, -8, v15
	v_ashrrev_i32_e32 v17, 31, v16
	v_add3_u32 v20, 0, v14, v19
	v_lshl_add_u64 v[14:15], v[16:17], 1, v[12:13]
	v_mul_lo_u32 v16, v16, s87
	v_mov_b32_e32 v99, v20
	global_load_dwordx4 v[80:83], v[14:15], off offset:2880
	v_add_u32_e32 v14, 0xa00, v18
	v_ashrrev_i32_e32 v14, 3, v14
	v_and_b32_e32 v14, -8, v14
	v_ashrrev_i32_e32 v15, 31, v14
	v_add3_u32 v20, 0, v16, v19
	v_lshl_add_u64 v[16:17], v[14:15], 1, v[12:13]
	v_add_u32_e32 v15, 0xc00, v18
	v_ashrrev_i32_e32 v15, 3, v15
	v_mul_lo_u32 v14, v14, s87
	v_mov_b32_e32 v100, v20
	global_load_dwordx4 v[84:87], v[16:17], off offset:2880
	v_and_b32_e32 v16, -8, v15
	v_ashrrev_i32_e32 v17, 31, v16
	v_add3_u32 v20, 0, v14, v19
	v_lshl_add_u64 v[14:15], v[16:17], 1, v[12:13]
	v_mul_lo_u32 v16, v16, s87
	v_add3_u32 v16, 0, v16, v19
	v_mov_b32_e32 v17, v0
	v_mov_b32_e32 v101, v20
	global_load_dwordx4 v[88:91], v[14:15], off offset:2880
	v_add_u32_e32 v14, 0xe00, v18
	v_ashrrev_i32_e32 v14, 3, v14
	v_and_b32_e32 v14, -8, v14
	v_ashrrev_i32_e32 v15, 31, v14
	v_lshl_add_u64 v[12:13], v[14:15], 1, v[12:13]
	v_mul_lo_u32 v1, v14, s87
	v_add3_u32 v1, 0, v1, v19
	v_mov_b32_e32 v102, v16
	global_load_dwordx4 v[92:95], v[12:13], off offset:2880
	v_lshlrev_b32_e32 v16, 8, v62
	v_lshl_add_u64 v[58:59], v[6:7], 0, v[16:17]
	v_add_co_u32_e64 v6, s[2:3], s10, v58
	v_mov_b32_e32 v13, v0
	s_nop 0
	v_addc_co_u32_e64 v7, s[2:3], 0, v59, s[2:3]
	v_mul_lo_u32 v12, v142, s16
	s_mov_b64 s[2:3], 0x17e00000
	v_lshl_add_u64 v[40:41], v[58:59], 0, s[2:3]
	v_readfirstlane_b32 s10, v3
	v_readfirstlane_b32 s3, v5
	v_readfirstlane_b32 s2, v4
	v_mov_b32_e32 v103, v1
	s_waitcnt vmcnt(7) lgkmcnt(0)
	ds_write_b16 v96, v64
	ds_write_b16_d16_hi v96, v64 offset:144
	ds_write_b16 v96, v65 offset:288
	ds_write_b16_d16_hi v96, v65 offset:432
	ds_write_b16 v96, v66 offset:576
	ds_write_b16_d16_hi v96, v66 offset:720
	ds_write_b16 v96, v67 offset:864
	ds_write_b16_d16_hi v96, v67 offset:1008
	s_waitcnt vmcnt(6)
	ds_write_b16 v97, v68
	ds_write_b16_d16_hi v97, v68 offset:144
	ds_write_b16 v97, v69 offset:288
	ds_write_b16_d16_hi v97, v69 offset:432
	ds_write_b16 v97, v70 offset:576
	ds_write_b16_d16_hi v97, v70 offset:720
	ds_write_b16 v97, v71 offset:864
	ds_write_b16_d16_hi v97, v71 offset:1008
	s_waitcnt vmcnt(5)
	ds_write_b16 v98, v72
	ds_write_b16_d16_hi v98, v72 offset:144
	ds_write_b16 v98, v73 offset:288
	ds_write_b16_d16_hi v98, v73 offset:432
	ds_write_b16 v98, v74 offset:576
	ds_write_b16_d16_hi v98, v74 offset:720
	ds_write_b16 v98, v75 offset:864
	ds_write_b16_d16_hi v98, v75 offset:1008
	s_waitcnt vmcnt(4)
; #define MFMA32(a, b, c) __builtin_amdgcn_mfma_f32_32x32x16_bf16((a), (b), (c), 0, 0, 0)
; __device__ __forceinline__ void ret_out_item(LAS unsigned char* lds, const bf16* Z, const bf16* AT, const float* gn, bf16* MIXED, int b, int c, const float* lgs) {
;     ...
;     for (int i = 0; i < 8; ++i) { const int ci = tid + 512 * i, l = ci & 63, ec = ci >> 6; const u32x4 vr = *(const u32x4*)(Z + (size_t)(rowbase + l) * NZ + ZC_RV + ec * 8);
; #pragma unroll
;         for (int e = 0; e < 4; ++e) { const unsigned vw = vr[e]; VT4[(8 * ec + 2 * e) * 72 + l] = (bf16)(vw & 0xffffu); VT4[(8 * ec + 2 * e + 1) * 72 + l] = (bf16)(vw >> 16); } }
;     __syncthreads();
;     const int hh = wid >> 1, lb = wid & 1, l = 32 * lb + r32, row = rowbase + l; const float lg = lgs[hh];
;     bf16x8 qf[8];
; #pragma unroll
;     for (int ds = 0; ds < 8; ++ds) qf[ds] = *(const bf16x8*)(Z + (size_t)row * NZ + ZC_RQ + hh * 128 + 16 * ds + 8 * hi);
;     f32x16 acc[4];
; #pragma unroll
;     for (int i = 0; i < 4; ++i)
; #pragma unroll
;         for (int r = 0; r < 16; ++r) acc[i][r] = 0.f;
;     const bf16* Sp = AT + (size_t)((b * 256 + c) * 4 + hh) * 16384;
; #pragma unroll
;     for (int eb = 0; eb < 4; ++eb)
; #pragma unroll
;         for (int ds = 0; ds < 8; ++ds) { const bf16x8 w = *(const bf16x8*)(Sp + (32 * eb + r32) * 128 + 16 * ds + 8 * hi);
;             acc[eb] = MFMA32(w, qf[ds], acc[eb]); if (ds == 3 || ds == 7) __builtin_amdgcn_sched_barrier(0); }
	ds_write_b16 v99, v76
	ds_write_b16_d16_hi v99, v76 offset:144
	ds_write_b16 v99, v77 offset:288
	ds_write_b16_d16_hi v99, v77 offset:432
	ds_write_b16 v99, v78 offset:576
	ds_write_b16_d16_hi v99, v78 offset:720
	ds_write_b16 v99, v79 offset:864
	ds_write_b16_d16_hi v99, v79 offset:1008
	s_waitcnt vmcnt(3)
	ds_write_b16 v100, v80
	ds_write_b16_d16_hi v100, v80 offset:144
	ds_write_b16 v100, v81 offset:288
	ds_write_b16_d16_hi v100, v81 offset:432
	ds_write_b16 v100, v82 offset:576
	ds_write_b16_d16_hi v100, v82 offset:720
	ds_write_b16 v100, v83 offset:864
	ds_write_b16_d16_hi v100, v83 offset:1008
	s_waitcnt vmcnt(2)
	ds_write_b16 v101, v84
	ds_write_b16_d16_hi v101, v84 offset:144
	ds_write_b16 v101, v85 offset:288
	ds_write_b16_d16_hi v101, v85 offset:432
	ds_write_b16 v101, v86 offset:576
	ds_write_b16_d16_hi v101, v86 offset:720
	ds_write_b16 v101, v87 offset:864
	ds_write_b16_d16_hi v101, v87 offset:1008
	s_waitcnt vmcnt(1)
	ds_write_b16 v102, v88
	ds_write_b16_d16_hi v102, v88 offset:144
	ds_write_b16 v102, v89 offset:288
	ds_write_b16_d16_hi v102, v89 offset:432
	ds_write_b16 v102, v90 offset:576
	ds_write_b16_d16_hi v102, v90 offset:720
	ds_write_b16 v102, v91 offset:864
	ds_write_b16_d16_hi v102, v91 offset:1008
	s_waitcnt vmcnt(0)
	ds_write_b16 v103, v92
	ds_write_b16_d16_hi v103, v92 offset:144
	ds_write_b16 v103, v93 offset:288
	ds_write_b16_d16_hi v103, v93 offset:432
	ds_write_b16 v103, v94 offset:576
	ds_write_b16_d16_hi v103, v94 offset:720
	ds_write_b16 v103, v95 offset:864
	ds_write_b16_d16_hi v103, v95 offset:1008
	s_waitcnt lgkmcnt(0)
	s_barrier
	global_load_dwordx4 v[6:9], v[6:7], off
	v_lshl_add_u64 v[10:11], v[12:13], 1, s[4:5]
	v_lshl_add_u64 v[10:11], v[10:11], 0, s[8:9]
	v_lshl_add_u64 v[38:39], v[10:11], 0, v[140:141]
	global_load_dwordx4 v[110:113], v[38:39], off offset:832
	global_load_dwordx4 v[10:13], v[40:41], off offset:32
	global_load_dwordx4 v[102:105], v[38:39], off offset:864
	global_load_dwordx4 v[14:17], v[40:41], off offset:64
	global_load_dwordx4 v[34:37], v[40:41], off offset:96
	global_load_dwordx4 v[106:109], v[38:39], off offset:896
	global_load_dwordx4 v[98:101], v[38:39], off offset:928
	global_load_dwordx4 v[94:97], v[38:39], off offset:960
	global_load_dwordx4 v[90:93], v[38:39], off offset:992
	global_load_dwordx4 v[86:89], v[38:39], off offset:1024
	global_load_dwordx4 v[82:85], v[38:39], off offset:1056
	v_cndmask_b32_e32 v1, v164, v42, vcc
	s_waitcnt vmcnt(0) lgkmcnt(0)
	v_mfma_f32_32x32x16_bf16 v[18:33], v[6:9], v[110:113], 0
	v_mfma_f32_32x32x16_bf16 v[18:33], v[10:13], v[102:105], v[18:33]
	v_mfma_f32_32x32x16_bf16 v[18:33], v[14:17], v[106:109], v[18:33]
	v_mfma_f32_32x32x16_bf16 v[18:33], v[34:37], v[98:101], v[18:33]
	global_load_dwordx4 v[2:5], v[40:41], off offset:128
	global_load_dwordx4 v[6:9], v[40:41], off offset:160
	s_waitcnt vmcnt(0) lgkmcnt(0)
	v_mfma_f32_32x32x16_bf16 v[18:33], v[2:5], v[94:97], v[18:33]
	global_load_dwordx4 v[2:5], v[40:41], off offset:192
	v_mfma_f32_32x32x16_bf16 v[18:33], v[6:9], v[90:93], v[18:33]
	global_load_dwordx4 v[6:9], v[40:41], off offset:224
	s_waitcnt vmcnt(0) lgkmcnt(0)
	v_mfma_f32_32x32x16_bf16 v[18:33], v[2:5], v[86:89], v[18:33]
	v_mfma_f32_32x32x16_bf16 v[18:33], v[6:9], v[82:85], v[18:33]
	s_mov_b32 s14, 0x17e02000
	v_add_co_u32_e32 v42, vcc, s14, v58
	s_nop 1
	v_addc_co_u32_e32 v43, vcc, 0, v59, vcc
	global_load_dwordx4 v[2:5], v[42:43], off
	global_load_dwordx4 v[34:37], v[42:43], off offset:32
	global_load_dwordx4 v[38:41], v[42:43], off offset:64
	s_waitcnt vmcnt(0) lgkmcnt(0)
	v_mfma_f32_32x32x16_bf16 v[2:17], v[2:5], v[110:113], 0
	v_mfma_f32_32x32x16_bf16 v[2:17], v[34:37], v[102:105], v[2:17]
	global_load_dwordx4 v[34:37], v[42:43], off offset:96
	v_mfma_f32_32x32x16_bf16 v[2:17], v[38:41], v[106:109], v[2:17]
	s_waitcnt vmcnt(0) lgkmcnt(0)
	v_mfma_f32_32x32x16_bf16 v[2:17], v[34:37], v[98:101], v[2:17]
	global_load_dwordx4 v[34:37], v[42:43], off offset:128
	global_load_dwordx4 v[38:41], v[42:43], off offset:160
	s_waitcnt vmcnt(0) lgkmcnt(0)
	v_mfma_f32_32x32x16_bf16 v[2:17], v[34:37], v[94:97], v[2:17]
	global_load_dwordx4 v[34:37], v[42:43], off offset:192
	v_mfma_f32_32x32x16_bf16 v[2:17], v[38:41], v[90:93], v[2:17]
	global_load_dwordx4 v[38:41], v[42:43], off offset:224
	s_waitcnt vmcnt(0) lgkmcnt(0)
	v_mfma_f32_32x32x16_bf16 v[2:17], v[34:37], v[86:89], v[2:17]
	v_mfma_f32_32x32x16_bf16 v[2:17], v[38:41], v[82:85], v[2:17]
	s_mov_b32 s14, 0x17e04000
	v_add_co_u32_e32 v60, vcc, s14, v58
	s_nop 1
	v_addc_co_u32_e32 v61, vcc, 0, v59, vcc
	global_load_dwordx4 v[34:37], v[60:61], off
	global_load_dwordx4 v[50:53], v[60:61], off offset:32
	global_load_dwordx4 v[54:57], v[60:61], off offset:64
	s_waitcnt vmcnt(0) lgkmcnt(0)
	v_mfma_f32_32x32x16_bf16 v[34:49], v[34:37], v[110:113], 0
	v_mfma_f32_32x32x16_bf16 v[34:49], v[50:53], v[102:105], v[34:49]
	global_load_dwordx4 v[50:53], v[60:61], off offset:96
	v_mfma_f32_32x32x16_bf16 v[34:49], v[54:57], v[106:109], v[34:49]
	s_waitcnt vmcnt(0) lgkmcnt(0)
	v_mfma_f32_32x32x16_bf16 v[34:49], v[50:53], v[98:101], v[34:49]
	global_load_dwordx4 v[50:53], v[60:61], off offset:128
	global_load_dwordx4 v[54:57], v[60:61], off offset:160
	s_waitcnt vmcnt(0) lgkmcnt(0)
	v_mfma_f32_32x32x16_bf16 v[34:49], v[50:53], v[94:97], v[34:49]
	global_load_dwordx4 v[50:53], v[60:61], off offset:192
	v_mfma_f32_32x32x16_bf16 v[34:49], v[54:57], v[90:93], v[34:49]
	global_load_dwordx4 v[54:57], v[60:61], off offset:224
	s_waitcnt vmcnt(0) lgkmcnt(0)
; __device__ __forceinline__ int crow(int r, int hi) { return (r & 3) + 8 * (r >> 2) + 4 * hi; }
; __device__ __forceinline__ float ex2f(float x) { return __builtin_amdgcn_exp2f(x); }
; #define MFMA32(a, b, c) __builtin_amdgcn_mfma_f32_32x32x16_bf16((a), (b), (c), 0, 0, 0)
; __device__ __forceinline__ void ret_out_item(LAS unsigned char* lds, const bf16* Z, const bf16* AT, const float* gn, bf16* MIXED, int b, int c, const float* lgs) {
;     ...
;         for (int ds = 0; ds < 8; ++ds) { const bf16x8 w = *(const bf16x8*)(Sp + (32 * eb + r32) * 128 + 16 * ds + 8 * hi);
;             acc[eb] = MFMA32(w, qf[ds], acc[eb]); if (ds == 3 || ds == 7) __builtin_amdgcn_sched_barrier(0); }
;     { const float qd = ex2f((float)(l + 1) * lg);
; #pragma unroll
;       for (int i = 0; i < 4; ++i)
; #pragma unroll
;           for (int r = 0; r < 16; ++r) acc[i][r] *= qd; }
; #pragma unroll
;     for (int mb = 0; mb < 2; ++mb) {
;         if (mb <= lb) {
;             f32x16 st;
; #pragma unroll
;             for (int r = 0; r < 16; ++r) st[r] = 0.f;
; #pragma unroll
;             for (int ds = 0; ds < 8; ++ds) { const bf16x8 kf = *(const bf16x8*)(Z + (size_t)(rowbase + 32 * mb + r32) * NZ + ZC_RK + hh * 128 + 16 * ds + 8 * hi); st = MFMA32(kf, qf[ds], st); }
; #pragma unroll
;             for (int r = 0; r < 16; ++r) { const int m = 32 * mb + crow(r, hi), diff = l - m; st[r] = diff >= 0 ? st[r] * ex2f((float)diff * lg) : 0.f; }
	v_mfma_f32_32x32x16_bf16 v[34:49], v[50:53], v[86:89], v[34:49]
	v_mfma_f32_32x32x16_bf16 v[34:49], v[54:57], v[82:85], v[34:49]
	s_mov_b32 s14, 0x17e06000
	v_add_co_u32_e32 v58, vcc, s14, v58
	s_nop 1
	v_addc_co_u32_e32 v59, vcc, 0, v59, vcc
	global_load_dwordx4 v[50:53], v[58:59], off
	global_load_dwordx4 v[54:57], v[58:59], off offset:32
	s_waitcnt vmcnt(0) lgkmcnt(0)
	v_mfma_f32_32x32x16_bf16 v[66:81], v[50:53], v[110:113], 0
	global_load_dwordx4 v[50:53], v[58:59], off offset:64
	v_mfma_f32_32x32x16_bf16 v[66:81], v[54:57], v[102:105], v[66:81]
	global_load_dwordx4 v[54:57], v[58:59], off offset:96
	s_waitcnt vmcnt(0) lgkmcnt(0)
	v_mfma_f32_32x32x16_bf16 v[66:81], v[50:53], v[106:109], v[66:81]
	v_mfma_f32_32x32x16_bf16 v[66:81], v[54:57], v[98:101], v[66:81]
	global_load_dwordx4 v[50:53], v[58:59], off offset:128
	global_load_dwordx4 v[54:57], v[58:59], off offset:160
	s_waitcnt vmcnt(0) lgkmcnt(0)
	v_mfma_f32_32x32x16_bf16 v[66:81], v[50:53], v[94:97], v[66:81]
	global_load_dwordx4 v[50:53], v[58:59], off offset:192
	v_mfma_f32_32x32x16_bf16 v[66:81], v[54:57], v[90:93], v[66:81]
	global_load_dwordx4 v[54:57], v[58:59], off offset:224
	s_waitcnt vmcnt(0) lgkmcnt(0)
	v_mfma_f32_32x32x16_bf16 v[66:81], v[50:53], v[86:89], v[66:81]
	v_mfma_f32_32x32x16_bf16 v[66:81], v[54:57], v[82:85], v[66:81]
	v_or_b32_e32 v50, s13, v62
	v_mul_lo_u32 v50, v50, s16
	v_mov_b32_e32 v51, v0
	v_lshl_add_u64 v[114:115], v[50:51], 1, s[4:5]
	v_lshl_add_u64 v[50:51], v[114:115], 0, s[8:9]
	v_lshl_add_u64 v[54:55], v[50:51], 0, v[140:141]
	global_load_dwordx4 v[50:53], v[54:55], off offset:1856
	global_load_dwordx4 v[116:119], v[54:55], off offset:1888
	global_load_dwordx4 v[120:123], v[54:55], off offset:1920
	global_load_dwordx4 v[124:127], v[54:55], off offset:1952
	global_load_dwordx4 v[128:131], v[54:55], off offset:1984
	global_load_dwordx4 v[132:135], v[54:55], off offset:2016
	global_load_dwordx4 v[178:181], v[54:55], off offset:2048
	global_load_dwordx4 v[182:185], v[54:55], off offset:2080
	v_add_u32_e32 v56, 1, v144
	v_cvt_f32_ubyte0_e32 v54, v56
	v_or_b32_e32 v137, s6, v62
	v_mul_f32_e32 v136, v1, v54
	v_mad_i32_i24 v145, v143, -4, -1
	v_mad_i32_i24 v187, v143, -4, v144
	v_mad_i32_i24 v146, v143, -4, -3
	v_mad_i32_i24 v147, v143, -4, -2
	v_mad_i32_i24 v148, v143, -4, -9
	v_mad_i32_i24 v149, v143, -4, -8
	v_add_u32_e32 v188, v144, v145
	v_mad_i32_i24 v150, v143, -4, -11
	v_mad_i32_i24 v151, v143, -4, -10
	v_cvt_f32_u32_e32 v189, v187
	v_add_u32_e32 v190, v144, v146
	v_add_u32_e32 v191, v144, v147
	v_add_u32_e32 v192, v144, v148
	v_add_u32_e32 v193, v144, v149
	v_cvt_f32_u32_e32 v204, v188
	v_add_u32_e32 v194, v144, v150
	v_add_u32_e32 v195, v144, v151
	v_cvt_f32_u32_e32 v205, v191
	v_cvt_f32_u32_e32 v206, v190
	v_cvt_f32_u32_e32 v207, v193
	v_cvt_f32_u32_e32 v208, v192
	v_mad_i32_i24 v154, v143, -4, v165
	v_mad_i32_i24 v155, v143, -4, -16
	v_cvt_f32_u32_e32 v209, v195
	v_cvt_f32_u32_e32 v210, v194
	v_add_u32_e32 v196, v144, v154
	v_add_u32_e32 v197, v144, v155
	v_cvt_f32_u32_e32 v211, v197
	v_cvt_f32_u32_e32 v212, v196
	v_mad_i32_i24 v156, v143, -4, v166
	v_mad_i32_i24 v158, v143, -4, v167
	v_add_u32_e32 v198, v144, v156
	v_add_u32_e32 v199, v144, v158
	v_cvt_f32_u32_e32 v213, v199
	v_cvt_f32_u32_e32 v214, v198
	v_cmp_lt_i32_e32 vcc, -1, v187
	v_mad_i32_i24 v159, v143, -4, v168
	v_mad_i32_i24 v160, v143, -4, v169
	v_add_u32_e32 v200, v144, v159
	v_add_u32_e32 v201, v144, v160
	v_mad_i32_i24 v176, v143, -4, v170
	v_mad_i32_i24 v177, v143, -4, v171
	v_cvt_f32_u32_e32 v215, v201
	v_cvt_f32_u32_e32 v216, v200
	v_add_u32_e32 v202, v144, v176
	v_add_u32_e32 v203, v144, v177
	v_add_u32_e32 v186, 0, v138
	v_cvt_f32_u32_e32 v217, v203
	v_cvt_f32_u32_e32 v218, v202
	v_exp_f32_e32 v136, v136
	s_cmp_eq_u32 s12, 0
	s_waitcnt vmcnt(0) lgkmcnt(0)
	v_mfma_f32_32x32x16_bf16 v[50:65], v[50:53], v[110:113], 0
	v_mul_f32_e64 v32, v136, v32
	v_mul_f32_e64 v33, v136, v33
	v_mul_f32_e64 v30, v136, v30
	v_mul_f32_e64 v31, v136, v31
	v_mul_f32_e64 v28, v136, v28
	v_mul_f32_e64 v29, v136, v29
	v_pk_mul_f32 v[26:27], v[136:137], v[26:27] op_sel_hi:[0,1]
	v_pk_mul_f32 v[24:25], v[136:137], v[24:25] op_sel_hi:[0,1]
	v_pk_mul_f32 v[22:23], v[136:137], v[22:23] op_sel_hi:[0,1]
	v_pk_mul_f32 v[20:21], v[136:137], v[20:21] op_sel_hi:[0,1]
	v_mfma_f32_32x32x16_bf16 v[50:65], v[116:119], v[102:105], v[50:65]
	v_mul_f32_e32 v116, v1, v189
	v_mul_f32_e32 v117, v1, v204
	v_exp_f32_e32 v116, v116
	v_mul_f32_e32 v118, v1, v205
	v_mul_f32_e32 v119, v1, v206
	v_mul_f32_e32 v189, v1, v207
	v_exp_f32_e32 v117, v117
	v_mfma_f32_32x32x16_bf16 v[50:65], v[120:123], v[106:109], v[50:65]
	v_mul_f32_e32 v121, v1, v208
	v_mul_f32_e32 v122, v1, v209
	v_mul_f32_e32 v123, v1, v210
	v_exp_f32_e32 v118, v118
	v_exp_f32_e32 v119, v119
	v_exp_f32_e32 v120, v189
	v_exp_f32_e32 v121, v121
	v_mfma_f32_32x32x16_bf16 v[50:65], v[124:127], v[98:101], v[50:65]
	v_exp_f32_e32 v122, v122
	v_exp_f32_e32 v123, v123
	v_mul_f32_e32 v204, v1, v211
	v_mul_f32_e32 v205, v1, v212
	v_exp_f32_e32 v124, v204
	v_exp_f32_e32 v125, v205
	v_mul_f32_e32 v206, v1, v213
	v_mfma_f32_32x32x16_bf16 v[50:65], v[128:131], v[94:97], v[50:65]
	v_mul_f32_e32 v207, v1, v214
	v_exp_f32_e32 v126, v206
	v_exp_f32_e32 v127, v207
	v_mul_f32_e32 v208, v1, v215
	v_mul_f32_e32 v209, v1, v216
	v_exp_f32_e32 v128, v208
	v_exp_f32_e32 v129, v209
	v_mfma_f32_32x32x16_bf16 v[50:65], v[132:135], v[90:93], v[50:65]
	v_mul_f32_e32 v210, v1, v217
	v_mul_f32_e32 v211, v1, v218
	v_exp_f32_e32 v130, v210
	v_exp_f32_e32 v131, v211
	v_pk_mul_f32 v[18:19], v[136:137], v[18:19] op_sel_hi:[0,1]
	v_pk_mul_f32 v[16:17], v[136:137], v[16:17] op_sel_hi:[0,1]
; #define LAS __attribute__((address_space(3)))
; __device__ __forceinline__ int crow(int r, int hi) { return (r & 3) + 8 * (r >> 2) + 4 * hi; }
; __device__ __forceinline__ float ex2f(float x) { return __builtin_amdgcn_exp2f(x); }
; #define MFMA32(a, b, c) __builtin_amdgcn_mfma_f32_32x32x16_bf16((a), (b), (c), 0, 0, 0)
; __device__ __forceinline__ void ret_out_item(LAS unsigned char* lds, const bf16* Z, const bf16* AT, const float* gn, bf16* MIXED, int b, int c, const float* lgs) {
;     ...
;     { const float qd = ex2f((float)(l + 1) * lg);
; #pragma unroll
;       for (int i = 0; i < 4; ++i)
; #pragma unroll
;           for (int r = 0; r < 16; ++r) acc[i][r] *= qd; }
; #pragma unroll
;     for (int mb = 0; mb < 2; ++mb) {
;         if (mb <= lb) {
;             f32x16 st;
; #pragma unroll
;             for (int r = 0; r < 16; ++r) st[r] = 0.f;
; #pragma unroll
;             for (int ds = 0; ds < 8; ++ds) { const bf16x8 kf = *(const bf16x8*)(Z + (size_t)(rowbase + 32 * mb + r32) * NZ + ZC_RK + hh * 128 + 16 * ds + 8 * hi); st = MFMA32(kf, qf[ds], st); }
; #pragma unroll
;             for (int r = 0; r < 16; ++r) { const int m = 32 * mb + crow(r, hi), diff = l - m; st[r] = diff >= 0 ? st[r] * ex2f((float)diff * lg) : 0.f; }
;             const bf16x8 pf0 = pack8(st, 0), pf1 = pack8(st, 8);
; #pragma unroll
;             for (int eb = 0; eb < 4; ++eb)
; #pragma unroll
;                 for (int kk = 0; kk < 2; ++kk) { const LAS bf16* vp = VT4 + (hh * 128 + 32 * eb + r32) * 72 + 16 * (2 * mb + kk) + 4 * hi;
;                     const u32x2 lo = *(const LAS u32x2*)vp, h2 = *(const LAS u32x2*)(vp + 8); const u32x4 v4 = (u32x4){lo.x, lo.y, h2.x, h2.y};
;                     acc[eb] = MFMA32(__builtin_bit_cast(bf16x8, v4), kk ? pf1 : pf0, acc[eb]); }
;         }
	v_pk_mul_f32 v[14:15], v[136:137], v[14:15] op_sel_hi:[0,1]
	v_mfma_f32_32x32x16_bf16 v[50:65], v[178:181], v[86:89], v[50:65]
	v_mul_f32_e64 v12, v136, v12
	v_mul_f32_e64 v13, v136, v13
	v_mul_f32_e64 v10, v136, v10
	v_mul_f32_e64 v11, v136, v11
	v_mul_f32_e64 v8, v136, v8
	v_mul_f32_e64 v9, v136, v9
	v_pk_mul_f32 v[6:7], v[136:137], v[6:7] op_sel_hi:[0,1]
	v_pk_mul_f32 v[4:5], v[136:137], v[4:5] op_sel_hi:[0,1]
	v_pk_mul_f32 v[2:3], v[136:137], v[2:3] op_sel_hi:[0,1]
	v_mfma_f32_32x32x16_bf16 v[50:65], v[182:185], v[82:85], v[50:65]
	s_nop 11
	v_pk_mul_f32 v[50:51], v[116:117], v[50:51]
	v_pk_mul_f32 v[52:53], v[118:119], v[52:53]
	v_pk_mul_f32 v[54:55], v[120:121], v[54:55]
	v_cvt_pk_bf16_f32 v50, v50, v51
	v_pk_mul_f32 v[56:57], v[122:123], v[56:57]
	v_cvt_pk_bf16_f32 v51, v52, v53
	v_cvt_pk_bf16_f32 v52, v54, v55
	v_cndmask_b32_e32 v55, 0, v50, vcc
	v_cmp_lt_i32_e32 vcc, -1, v191
	v_cvt_pk_bf16_f32 v53, v56, v57
	v_pk_mul_f32 v[58:59], v[124:125], v[58:59]
	v_cndmask_b32_e32 v56, 0, v51, vcc
	v_cmp_lt_i32_e32 vcc, -1, v193
	v_cvt_pk_bf16_f32 v54, v58, v59
	v_lshrrev_b32_e32 v50, 16, v50
	v_cndmask_b32_e32 v57, 0, v52, vcc
	v_cmp_lt_i32_e32 vcc, -1, v195
	v_lshrrev_b32_e32 v51, 16, v51
	v_lshrrev_b32_e32 v52, 16, v52
	v_cndmask_b32_e32 v58, 0, v53, vcc
	v_cmp_lt_i32_e32 vcc, -1, v197
	v_lshrrev_b32_e32 v53, 16, v53
	v_pk_mul_f32 v[60:61], v[126:127], v[60:61]
	v_cndmask_b32_e32 v59, 0, v54, vcc
	v_cmp_lt_i32_e32 vcc, -1, v188
	v_lshrrev_b32_e32 v54, 16, v54
	v_pk_mul_f32 v[62:63], v[128:129], v[62:63]
	v_cndmask_b32_e32 v50, 0, v50, vcc
	v_cmp_lt_i32_e32 vcc, -1, v190
	v_perm_b32 v116, v50, v55, s91
	v_cvt_pk_bf16_f32 v50, v60, v61
	v_cndmask_b32_e32 v51, 0, v51, vcc
	v_cmp_lt_i32_e32 vcc, -1, v192
	v_perm_b32 v117, v51, v56, s91
	v_pk_mul_f32 v[64:65], v[130:131], v[64:65]
	v_cndmask_b32_e32 v52, 0, v52, vcc
	v_cmp_lt_i32_e32 vcc, -1, v194
	v_perm_b32 v118, v52, v57, s91
	v_pk_mul_f32 v[60:61], v[136:137], v[44:45] op_sel_hi:[0,1]
	v_cndmask_b32_e32 v53, 0, v53, vcc
	v_cmp_lt_i32_e32 vcc, -1, v196
	v_perm_b32 v119, v53, v58, s91
	v_cvt_pk_bf16_f32 v58, v64, v65
	v_cndmask_b32_e32 v54, 0, v54, vcc
	v_cmp_lt_i32_e32 vcc, -1, v199
	v_perm_b32 v120, v54, v59, s91
	v_cvt_pk_bf16_f32 v54, v62, v63
	v_cndmask_b32_e32 v51, 0, v50, vcc
	v_lshrrev_b32_e32 v50, 16, v50
	v_cmp_lt_i32_e32 vcc, -1, v198
	v_pk_mul_f32 v[64:65], v[136:137], v[48:49] op_sel_hi:[0,1]
	v_pk_mul_f32 v[62:63], v[136:137], v[46:47] op_sel_hi:[0,1]
	v_cndmask_b32_e32 v50, 0, v50, vcc
	v_perm_b32 v121, v50, v51, s91
	v_mul_lo_u32 v50, v137, s87
	v_add_u32_e32 v181, v186, v50
	ds_read2_b64 v[50:53], v181 offset1:2
	v_cmp_lt_i32_e32 vcc, -1, v201
	s_waitcnt lgkmcnt(0)
	v_mfma_f32_32x32x16_bf16 v[18:33], v[50:53], v[116:119], v[18:33]
	v_cndmask_b32_e32 v55, 0, v54, vcc
	v_lshrrev_b32_e32 v54, 16, v54
	v_cmp_lt_i32_e32 vcc, -1, v200
	v_lshrrev_b32_e32 v51, 16, v58
	v_add_u32_e32 v178, 0x1000, v181
	v_cndmask_b32_e32 v54, 0, v54, vcc
	v_cmp_lt_i32_e32 vcc, -1, v203
	v_perm_b32 v122, v54, v55, s91
	ds_read2_b64 v[54:57], v181 offset0:4 offset1:6
	v_cndmask_b32_e32 v50, 0, v58, vcc
	v_cmp_lt_i32_e32 vcc, -1, v202
	v_add_u32_e32 v179, 0x2000, v181
	ds_read2_b64 v[124:127], v179 offset0:128 offset1:130
	v_cndmask_b32_e32 v51, 0, v51, vcc
	v_perm_b32 v123, v51, v50, s91
	ds_read2_b64 v[50:53], v178 offset0:64 offset1:66
	s_waitcnt lgkmcnt(0)
	v_mfma_f32_32x32x16_bf16 v[2:17], v[50:53], v[116:119], v[2:17]
	ds_read2_b64 v[50:53], v178 offset0:68 offset1:70
	v_mul_f32_e64 v58, v136, v42
	v_mul_f32_e64 v59, v136, v43
	v_add_u32_e32 v180, 0x3000, v181
	v_mul_f32_e64 v48, v136, v80
	v_mul_f32_e64 v49, v136, v81
	v_pk_mul_f32 v[46:47], v[136:137], v[78:79] op_sel_hi:[0,1]
	v_pk_mul_f32 v[44:45], v[136:137], v[76:77] op_sel_hi:[0,1]
	v_pk_mul_f32 v[42:43], v[136:137], v[74:75] op_sel_hi:[0,1]
	v_mfma_f32_32x32x16_bf16 v[18:33], v[54:57], v[120:123], v[18:33]
	v_mul_f32_e64 v56, v136, v40
	v_mul_f32_e64 v57, v136, v41
	v_mul_f32_e64 v54, v136, v38
	v_mul_f32_e64 v55, v136, v39
	v_mul_f32_e64 v40, v136, v72
	v_mul_f32_e64 v41, v136, v73
	v_pk_mul_f32 v[38:39], v[136:137], v[70:71] op_sel_hi:[0,1]
	s_waitcnt lgkmcnt(0)
	v_mfma_f32_32x32x16_bf16 v[2:17], v[50:53], v[120:123], v[2:17]
	v_mul_f32_e64 v52, v136, v36
	v_mul_f32_e64 v53, v136, v37
	v_mul_f32_e64 v50, v136, v34
	v_mul_f32_e64 v51, v136, v35
	ds_read2_b64 v[34:37], v179 offset0:132 offset1:134
	s_nop 0
	v_mfma_f32_32x32x16_bf16 v[50:65], v[124:127], v[116:119], v[50:65]
	ds_read2_b64 v[124:127], v180 offset0:192 offset1:194
	s_waitcnt lgkmcnt(1)
	v_mfma_f32_32x32x16_bf16 v[50:65], v[34:37], v[120:123], v[50:65]
	v_mul_f32_e64 v36, v136, v68
	v_mul_f32_e64 v37, v136, v69
	v_mul_f32_e64 v34, v136, v66
	v_mul_f32_e64 v35, v136, v67
	ds_read2_b64 v[66:69], v180 offset0:196 offset1:198
	s_waitcnt lgkmcnt(1)
	v_mfma_f32_32x32x16_bf16 v[34:49], v[124:127], v[116:119], v[34:49]
	s_waitcnt lgkmcnt(0)
	v_mfma_f32_32x32x16_bf16 v[34:49], v[66:69], v[120:123], v[34:49]
	s_cbranch_scc1 .LBB0_681
; #define LAS __attribute__((address_space(3)))
; __device__ __forceinline__ int crow(int r, int hi) { return (r & 3) + 8 * (r >> 2) + 4 * hi; }
; __device__ __forceinline__ float ex2f(float x) { return __builtin_amdgcn_exp2f(x); }
; #define MFMA32(a, b, c) __builtin_amdgcn_mfma_f32_32x32x16_bf16((a), (b), (c), 0, 0, 0)
; __device__ __forceinline__ void ret_out_item(LAS unsigned char* lds, const bf16* Z, const bf16* AT, const float* gn, bf16* MIXED, int b, int c, const float* lgs) {
;     ...
;     for (int mb = 0; mb < 2; ++mb) {
;         if (mb <= lb) {
;             f32x16 st;
; #pragma unroll
;             for (int r = 0; r < 16; ++r) st[r] = 0.f;
; #pragma unroll
;             for (int ds = 0; ds < 8; ++ds) { const bf16x8 kf = *(const bf16x8*)(Z + (size_t)(rowbase + 32 * mb + r32) * NZ + ZC_RK + hh * 128 + 16 * ds + 8 * hi); st = MFMA32(kf, qf[ds], st); }
; #pragma unroll
;             for (int r = 0; r < 16; ++r) { const int m = 32 * mb + crow(r, hi), diff = l - m; st[r] = diff >= 0 ? st[r] * ex2f((float)diff * lg) : 0.f; }
;             const bf16x8 pf0 = pack8(st, 0), pf1 = pack8(st, 8);
; #pragma unroll
;             for (int eb = 0; eb < 4; ++eb)
; #pragma unroll
;                 for (int kk = 0; kk < 2; ++kk) { const LAS bf16* vp = VT4 + (hh * 128 + 32 * eb + r32) * 72 + 16 * (2 * mb + kk) + 4 * hi;
;                     const u32x2 lo = *(const LAS u32x2*)vp, h2 = *(const LAS u32x2*)(vp + 8); const u32x4 v4 = (u32x4){lo.x, lo.y, h2.x, h2.y};
;                     acc[eb] = MFMA32(__builtin_bit_cast(bf16x8, v4), kk ? pf1 : pf0, acc[eb]); }
;         }
	v_lshl_add_u64 v[66:67], s[6:7], 1, v[114:115]
	v_lshlrev_b32_e32 v68, 1, v138
	v_mov_b32_e32 v69, v0
	v_lshl_add_u64 v[70:71], v[66:67], 0, v[68:69]
	v_add_co_u32_e32 v66, vcc, 0x28000, v70
	s_mov_b64 s[12:13], 0x28740
	s_nop 0
	v_addc_co_u32_e32 v67, vcc, 0, v71, vcc
	global_load_dwordx4 v[66:69], v[66:67], off offset:1856
	v_lshl_add_u64 v[70:71], v[70:71], 0, s[12:13]
	global_load_dwordx4 v[182:185], v[70:71], off offset:32
	global_load_dwordx4 v[134:137], v[70:71], off offset:64
	global_load_dwordx4 v[130:133], v[70:71], off offset:96
	global_load_dwordx4 v[126:129], v[70:71], off offset:128
	global_load_dwordx4 v[122:125], v[70:71], off offset:160
	global_load_dwordx4 v[118:121], v[70:71], off offset:192
	global_load_dwordx4 v[114:117], v[70:71], off offset:224
	v_mul_i32_i24_e32 v70, -4, v143
	v_subrev_u32_e32 v143, 32, v144
	v_add_u32_e32 v144, v143, v145
	v_add_u32_e32 v145, v143, v70
	v_add_u32_e32 v146, v143, v146
	v_add_u32_e32 v147, v143, v147
	v_add_u32_e32 v148, v143, v148
	v_add_u32_e32 v149, v143, v149
	v_add_u32_e32 v150, v143, v150
	v_add_u32_e32 v151, v143, v151
	v_add_u32_e32 v154, v143, v154
	v_add_u32_e32 v155, v143, v155
	v_add_u32_e32 v156, v143, v156
	v_add_u32_e32 v158, v143, v158
	v_add_u32_e32 v159, v143, v159
	v_add_u32_e32 v160, v143, v160
	v_add_u32_e32 v176, v143, v176
	ds_read2_b64 v[186:189], v181 offset0:8 offset1:10
	ds_read2_b64 v[190:193], v181 offset0:12 offset1:14
	ds_read2_b64 v[194:197], v178 offset0:72 offset1:74
	ds_read2_b64 v[198:201], v179 offset0:136 offset1:138
	v_cvt_f32_u32_e32 v181, v148
	v_cmp_lt_i32_e32 vcc, -1, v145
	s_waitcnt vmcnt(0) lgkmcnt(0)
	v_mfma_f32_32x32x16_bf16 v[66:81], v[66:69], v[110:113], 0
	v_cvt_f32_u32_e32 v111, v145
	v_cvt_f32_u32_e32 v112, v144
	v_add_u32_e32 v110, v143, v177
	v_cvt_f32_u32_e32 v113, v147
	v_cvt_f32_u32_e32 v143, v146
	v_cvt_f32_u32_e32 v177, v149
	v_mfma_f32_32x32x16_bf16 v[66:81], v[182:185], v[102:105], v[66:81]
	v_cvt_f32_u32_e32 v102, v151
	v_cvt_f32_u32_e32 v103, v150
	v_cvt_f32_u32_e32 v104, v155
	v_cvt_f32_u32_e32 v105, v154
	v_cvt_f32_u32_e32 v182, v158
	v_cvt_f32_u32_e32 v183, v156
	v_cvt_f32_u32_e32 v184, v160
	v_mfma_f32_32x32x16_bf16 v[66:81], v[134:137], v[106:109], v[66:81]
	v_mul_f32_e32 v109, v1, v111
	v_mul_f32_e32 v111, v1, v112
	v_cvt_f32_u32_e32 v106, v159
	v_cvt_f32_u32_e32 v107, v110
	v_cvt_f32_u32_e32 v108, v176
	v_mul_f32_e32 v112, v1, v113
	v_mul_f32_e32 v113, v1, v143
	v_mfma_f32_32x32x16_bf16 v[66:81], v[130:133], v[98:101], v[66:81]
	v_mul_f32_e32 v98, v1, v177
	v_mul_f32_e32 v99, v1, v181
	v_mul_f32_e32 v100, v1, v102
	v_mul_f32_e32 v101, v1, v103
	v_mul_f32_e32 v102, v1, v104
	v_mul_f32_e32 v103, v1, v105
	v_mul_f32_e32 v104, v1, v182
	v_mfma_f32_32x32x16_bf16 v[66:81], v[126:129], v[94:97], v[66:81]
	v_exp_f32_e32 v94, v109
	v_exp_f32_e32 v95, v111
	v_mul_f32_e32 v105, v1, v183
	v_exp_f32_e32 v96, v100
	v_exp_f32_e32 v97, v101
	v_mul_f32_e32 v126, v1, v184
	v_mul_f32_e32 v106, v1, v106
	v_mfma_f32_32x32x16_bf16 v[66:81], v[122:125], v[90:93], v[66:81]
	v_exp_f32_e32 v90, v112
	v_exp_f32_e32 v91, v113
	v_exp_f32_e32 v92, v98
	v_exp_f32_e32 v93, v99
	v_exp_f32_e32 v98, v102
	v_exp_f32_e32 v99, v103
	v_mul_f32_e32 v107, v1, v107
	v_mfma_f32_32x32x16_bf16 v[66:81], v[118:121], v[86:89], v[66:81]
	v_mul_f32_e32 v1, v1, v108
	v_exp_f32_e32 v86, v104
	v_exp_f32_e32 v87, v105
	v_exp_f32_e32 v101, v1
	v_exp_f32_e32 v88, v126
	v_exp_f32_e32 v89, v106
	v_exp_f32_e32 v100, v107
	v_mfma_f32_32x32x16_bf16 v[66:81], v[114:117], v[82:85], v[66:81]
	s_nop 11
	v_pk_mul_f32 v[66:67], v[94:95], v[66:67]
	v_pk_mul_f32 v[68:69], v[90:91], v[68:69]
	v_cvt_pk_bf16_f32 v1, v66, v67
	v_pk_mul_f32 v[70:71], v[92:93], v[70:71]
	v_pk_mul_f32 v[74:75], v[98:99], v[74:75]
	v_cvt_pk_bf16_f32 v66, v68, v69
	v_cndmask_b32_e32 v69, 0, v1, vcc
	v_cmp_lt_i32_e32 vcc, -1, v147
	v_pk_mul_f32 v[72:73], v[96:97], v[72:73]
	v_cvt_pk_bf16_f32 v67, v70, v71
	v_cvt_pk_bf16_f32 v70, v74, v75
	v_cndmask_b32_e32 v74, 0, v66, vcc
	v_cmp_lt_i32_e32 vcc, -1, v149
	v_pk_mul_f32 v[76:77], v[86:87], v[76:77]
	v_cvt_pk_bf16_f32 v68, v72, v73
	v_cndmask_b32_e32 v75, 0, v67, vcc
	v_cmp_lt_i32_e32 vcc, -1, v151
	v_cvt_pk_bf16_f32 v71, v76, v77
	v_lshrrev_b32_e32 v1, 16, v1
	v_cndmask_b32_e32 v76, 0, v68, vcc
	v_cmp_lt_i32_e32 vcc, -1, v155
	v_pk_mul_f32 v[78:79], v[88:89], v[78:79]
	v_lshrrev_b32_e32 v66, 16, v66
	v_cndmask_b32_e32 v77, 0, v70, vcc
	v_cmp_lt_i32_e32 vcc, -1, v144
	v_cvt_pk_bf16_f32 v72, v78, v79
	v_lshrrev_b32_e32 v67, 16, v67
	v_cndmask_b32_e32 v1, 0, v1, vcc
	v_cmp_lt_i32_e32 vcc, -1, v146
	v_pk_mul_f32 v[80:81], v[100:101], v[80:81]
	v_lshrrev_b32_e32 v68, 16, v68
	v_cndmask_b32_e32 v78, 0, v66, vcc
	v_cmp_lt_i32_e32 vcc, -1, v148
	v_cvt_pk_bf16_f32 v73, v80, v81
	v_perm_b32 v66, v1, v69, s91
	v_cndmask_b32_e32 v79, 0, v67, vcc
	v_cmp_lt_i32_e32 vcc, -1, v150
	v_perm_b32 v67, v78, v74, s91
	v_lshrrev_b32_e32 v1, 16, v70
	v_cndmask_b32_e32 v80, 0, v68, vcc
	v_cmp_lt_i32_e32 vcc, -1, v158
	v_perm_b32 v68, v79, v75, s91
	v_perm_b32 v69, v80, v76, s91
	v_cndmask_b32_e32 v74, 0, v71, vcc
	v_cmp_lt_i32_e32 vcc, -1, v160
	v_lshrrev_b32_e32 v70, 16, v71
	v_lshrrev_b32_e32 v71, 16, v72
	v_cndmask_b32_e32 v75, 0, v72, vcc
	v_cmp_lt_i32_e32 vcc, -1, v110
	v_lshrrev_b32_e32 v72, 16, v73
	v_mfma_f32_32x32x16_bf16 v[2:17], v[194:197], v[66:69], v[2:17]
	v_cndmask_b32_e32 v76, 0, v73, vcc
	v_cmp_lt_i32_e32 vcc, -1, v154
	s_nop 1
	v_cndmask_b32_e32 v1, 0, v1, vcc
	v_cmp_lt_i32_e32 vcc, -1, v156
	v_mfma_f32_32x32x16_bf16 v[50:65], v[198:201], v[66:69], v[50:65]
	s_nop 0
	v_cndmask_b32_e32 v73, 0, v70, vcc
	v_cmp_lt_i32_e32 vcc, -1, v159
	v_perm_b32 v70, v1, v77, s91
	s_nop 0
	v_cndmask_b32_e32 v78, 0, v71, vcc
	v_cmp_lt_i32_e32 vcc, -1, v176
	v_perm_b32 v71, v73, v74, s91
	v_mfma_f32_32x32x16_bf16 v[18:33], v[186:189], v[66:69], v[18:33]
	v_cndmask_b32_e32 v79, 0, v72, vcc
	v_perm_b32 v72, v78, v75, s91
	v_perm_b32 v73, v79, v76, s91
	ds_read2_b64 v[74:77], v178 offset0:76 offset1:78
	s_waitcnt lgkmcnt(0)
	v_mfma_f32_32x32x16_bf16 v[2:17], v[74:77], v[70:73], v[2:17]
	ds_read2_b64 v[74:77], v179 offset0:140 offset1:142
	s_waitcnt lgkmcnt(0)
	v_mfma_f32_32x32x16_bf16 v[50:65], v[74:77], v[70:73], v[50:65]
	ds_read2_b64 v[74:77], v180 offset0:200 offset1:202
	s_waitcnt lgkmcnt(0)
	v_mfma_f32_32x32x16_bf16 v[34:49], v[74:77], v[66:69], v[34:49]
	ds_read2_b64 v[66:69], v180 offset0:204 offset1:206
	v_mfma_f32_32x32x16_bf16 v[18:33], v[190:193], v[70:73], v[18:33]
	s_waitcnt lgkmcnt(0)
	v_mfma_f32_32x32x16_bf16 v[34:49], v[66:69], v[70:73], v[34:49]
